# phase 1 (h0 = bf16(x*(1+scale)+shift)) hand-written for 256 workgroups: 8 rows of loads in flight, modulation vectors prefetched per batch
# speedup vs baseline: 1.0070x; 1.0070x over previous
.LBB0_165:
	s_or_b64 exec, exec, s[0:1]
	s_waitcnt lgkmcnt(0)
	v_mov_b32_e32 v0, v254
	s_mov_b32 s3, 0
	s_barrier
	s_lshl_b64 s[4:5], s[2:3], 9
	v_ashrrev_i32_e32 v1, 31, v0
	v_lshl_add_u64 v[32:33], s[4:5], 0, v[0:1]
	s_mov_b64 s[0:1], 0x400000
	v_cmp_gt_u64_e32 vcc, s[0:1], v[32:33]
	s_and_saveexec_b64 s[12:13], vcc
	s_cbranch_execz .LBB0_180
	s_lshl_b64 s[8:9], s[2:3], 13
	s_mov_b32 s6, s30
	s_mov_b32 s7, s3
	v_lshl_add_u64 v[34:35], v[0:1], 4, s[8:9]
	s_lshl_b64 s[8:9], s[2:3], 12
	s_lshl_b64 s[18:19], s[6:7], 9
	s_lshl_b64 s[22:23], s[6:7], 11
	s_lshl_b64 s[24:25], s[6:7], 15
	v_lshl_add_u64 v[36:37], v[0:1], 3, s[8:9]
	s_lshl_b64 s[50:51], s[6:7], 14
	s_lshl_b64 s[56:57], s[6:7], 10
	s_lshl_b64 s[8:9], s[2:3], 14
	s_lshl_b64 s[60:61], s[6:7], 16
	s_add_u32 s6, s56, s4
	v_lshlrev_b64 v[2:3], 5, v[0:1]
	s_addc_u32 s7, s57, s5
	v_lshl_add_u64 v[38:39], s[8:9], 0, v[2:3]
	v_lshl_add_u64 v[2:3], s[6:7], 0, v[0:1]
	s_add_u32 s6, s4, s18
	s_mul_i32 s66, s30, 0x600
	s_addc_u32 s7, s5, s19
	s_mul_hi_u32 s67, s30, 0x600
	s_add_u32 s4, s66, s4
	s_addc_u32 s5, s67, s5
	v_lshlrev_b64 v[40:41], 5, v[2:3]
	v_lshlrev_b64 v[42:43], 4, v[2:3]
	v_lshl_add_u64 v[2:3], s[6:7], 0, v[0:1]
	v_lshl_add_u64 v[0:1], s[4:5], 0, v[0:1]
	v_lshlrev_b64 v[46:47], 5, v[0:1]
	v_or_b32_e32 v40, 16, v40
	v_lshlrev_b64 v[44:45], 5, v[2:3]
	v_or_b32_e32 v46, 16, v46
	v_lshlrev_b64 v[48:49], 4, v[0:1]
	v_lshlrev_b64 v[50:51], 4, v[2:3]
	s_mov_b64 s[74:75], 0
	v_mov_b32_e32 v53, 0
	s_movk_i32 s3, 0x3000
	s_mov_b64 s[76:77], 0x1000
	s_movk_i32 s86, 0x1000
	s_mov_b64 s[78:79], 0x3fffff
	s_mov_b64 s[80:81], s[36:37]
	s_mov_b64 s[82:83], s[28:29]
	s_cmp_lg_u32 s30, 0x100
	s_cbranch_scc1 .Lp1_orig
	s_lshl_b32 s74, s2, 9
	v_add_u32_e32 v60, s74, v254
	v_lshlrev_b32_e32 v61, 4, v60
	v_lshlrev_b32_e32 v60, 5, v60
	v_and_b32_e32 v62, 0x7f, v254
	v_lshlrev_b32_e32 v62, 5, v62
	s_mov_b32 s80, s36
	s_mov_b32 s81, s37
	s_add_u32 s4, s28, 0x15c00000
	s_addc_u32 s5, s29, 0
	s_mov_b32 s6, s28
	s_mov_b32 s7, s29
	s_add_u32 s8, s28, 0x1000
	s_addc_u32 s9, s29, 0
	global_load_dwordx4 v[128:131], v62, s[6:7]
	global_load_dwordx4 v[132:135], v62, s[6:7] offset:16
	global_load_dwordx4 v[136:139], v62, s[8:9]
	global_load_dwordx4 v[140:143], v62, s[8:9] offset:16
	s_add_u32 s6, s6, 0x3000
	s_addc_u32 s7, s7, 0
	s_add_u32 s8, s8, 0x3000
	s_addc_u32 s9, s9, 0
	global_load_dwordx4 v[64:67], v60, s[80:81] nt
	global_load_dwordx4 v[68:71], v60, s[80:81] offset:16 nt
	s_add_u32 s80, s80, 0x400000
	s_addc_u32 s81, s81, 0
	global_load_dwordx4 v[72:75], v60, s[80:81] nt
	global_load_dwordx4 v[76:79], v60, s[80:81] offset:16 nt
	s_add_u32 s80, s80, 0x400000
	s_addc_u32 s81, s81, 0
	global_load_dwordx4 v[80:83], v60, s[80:81] nt
	global_load_dwordx4 v[84:87], v60, s[80:81] offset:16 nt
	s_add_u32 s80, s80, 0x400000
	s_addc_u32 s81, s81, 0
	global_load_dwordx4 v[88:91], v60, s[80:81] nt
	global_load_dwordx4 v[92:95], v60, s[80:81] offset:16 nt
	s_add_u32 s80, s80, 0x400000
	s_addc_u32 s81, s81, 0
	global_load_dwordx4 v[96:99], v60, s[80:81] nt
	global_load_dwordx4 v[100:103], v60, s[80:81] offset:16 nt
	s_add_u32 s80, s80, 0x400000
	s_addc_u32 s81, s81, 0
	global_load_dwordx4 v[104:107], v60, s[80:81] nt
	global_load_dwordx4 v[108:111], v60, s[80:81] offset:16 nt
	s_add_u32 s80, s80, 0x400000
	s_addc_u32 s81, s81, 0
	global_load_dwordx4 v[112:115], v60, s[80:81] nt
	global_load_dwordx4 v[116:119], v60, s[80:81] offset:16 nt
	s_add_u32 s80, s80, 0x400000
	s_addc_u32 s81, s81, 0
	global_load_dwordx4 v[120:123], v60, s[80:81] nt
	global_load_dwordx4 v[124:127], v60, s[80:81] offset:16 nt
	s_add_u32 s80, s80, 0x400000
	s_addc_u32 s81, s81, 0
	global_load_dwordx4 v[144:147], v62, s[6:7]
	global_load_dwordx4 v[148:151], v62, s[6:7] offset:16
	global_load_dwordx4 v[152:155], v62, s[8:9]
	global_load_dwordx4 v[156:159], v62, s[8:9] offset:16
	s_add_u32 s6, s6, 0x3000
	s_addc_u32 s7, s7, 0
	s_add_u32 s8, s8, 0x3000
	s_addc_u32 s9, s9, 0
	s_waitcnt vmcnt(20)
	v_add_f32_e32 v136, 1.0, v136
	v_add_f32_e32 v137, 1.0, v137
	v_add_f32_e32 v138, 1.0, v138
	v_add_f32_e32 v139, 1.0, v139
	v_add_f32_e32 v140, 1.0, v140
	v_add_f32_e32 v141, 1.0, v141
	v_add_f32_e32 v142, 1.0, v142
	v_add_f32_e32 v143, 1.0, v143
	s_waitcnt vmcnt(18)
	v_fma_f32 v64, v64, v136, v128
	v_fma_f32 v65, v65, v137, v129
	v_fma_f32 v66, v66, v138, v130
	v_fma_f32 v67, v67, v139, v131
	v_fma_f32 v68, v68, v140, v132
	v_fma_f32 v69, v69, v141, v133
	v_fma_f32 v70, v70, v142, v134
	v_fma_f32 v71, v71, v143, v135
	v_cvt_pk_bf16_f32 v64, v64, v65
	v_cvt_pk_bf16_f32 v65, v66, v67
	v_cvt_pk_bf16_f32 v66, v68, v69
	v_cvt_pk_bf16_f32 v67, v70, v71
	global_store_dwordx4 v61, v[64:67], s[4:5]
	s_add_u32 s4, s4, 0x200000
	s_addc_u32 s5, s5, 0
	global_load_dwordx4 v[64:67], v60, s[80:81] nt
	global_load_dwordx4 v[68:71], v60, s[80:81] offset:16 nt
	s_add_u32 s80, s80, 0x400000
	s_addc_u32 s81, s81, 0
	s_waitcnt vmcnt(19)
	v_fma_f32 v72, v72, v136, v128
	v_fma_f32 v73, v73, v137, v129
	v_fma_f32 v74, v74, v138, v130
	v_fma_f32 v75, v75, v139, v131
	v_fma_f32 v76, v76, v140, v132
	v_fma_f32 v77, v77, v141, v133
	v_fma_f32 v78, v78, v142, v134
	v_fma_f32 v79, v79, v143, v135
	v_cvt_pk_bf16_f32 v72, v72, v73
	v_cvt_pk_bf16_f32 v73, v74, v75
	v_cvt_pk_bf16_f32 v74, v76, v77
	v_cvt_pk_bf16_f32 v75, v78, v79
	global_store_dwordx4 v61, v[72:75], s[4:5]
	s_add_u32 s4, s4, 0x200000
	s_addc_u32 s5, s5, 0
	global_load_dwordx4 v[72:75], v60, s[80:81] nt
	global_load_dwordx4 v[76:79], v60, s[80:81] offset:16 nt
	s_add_u32 s80, s80, 0x400000
	s_addc_u32 s81, s81, 0
	s_waitcnt vmcnt(20)
	v_fma_f32 v80, v80, v136, v128
	v_fma_f32 v81, v81, v137, v129
	v_fma_f32 v82, v82, v138, v130
	v_fma_f32 v83, v83, v139, v131
	v_fma_f32 v84, v84, v140, v132
	v_fma_f32 v85, v85, v141, v133
	v_fma_f32 v86, v86, v142, v134
	v_fma_f32 v87, v87, v143, v135
	v_cvt_pk_bf16_f32 v80, v80, v81
	v_cvt_pk_bf16_f32 v81, v82, v83
	v_cvt_pk_bf16_f32 v82, v84, v85
	v_cvt_pk_bf16_f32 v83, v86, v87
	global_store_dwordx4 v61, v[80:83], s[4:5]
	s_add_u32 s4, s4, 0x200000
	s_addc_u32 s5, s5, 0
	global_load_dwordx4 v[80:83], v60, s[80:81] nt
	global_load_dwordx4 v[84:87], v60, s[80:81] offset:16 nt
	s_add_u32 s80, s80, 0x400000
	s_addc_u32 s81, s81, 0
	s_waitcnt vmcnt(21)
	v_fma_f32 v88, v88, v136, v128
	v_fma_f32 v89, v89, v137, v129
	v_fma_f32 v90, v90, v138, v130
	v_fma_f32 v91, v91, v139, v131
	v_fma_f32 v92, v92, v140, v132
	v_fma_f32 v93, v93, v141, v133
	v_fma_f32 v94, v94, v142, v134
	v_fma_f32 v95, v95, v143, v135
	v_cvt_pk_bf16_f32 v88, v88, v89
	v_cvt_pk_bf16_f32 v89, v90, v91
	v_cvt_pk_bf16_f32 v90, v92, v93
	v_cvt_pk_bf16_f32 v91, v94, v95
	global_store_dwordx4 v61, v[88:91], s[4:5]
	s_add_u32 s4, s4, 0x200000
	s_addc_u32 s5, s5, 0
	global_load_dwordx4 v[88:91], v60, s[80:81] nt
	global_load_dwordx4 v[92:95], v60, s[80:81] offset:16 nt
	s_add_u32 s80, s80, 0x400000
	s_addc_u32 s81, s81, 0
	global_load_dwordx4 v[128:131], v62, s[6:7]
	global_load_dwordx4 v[132:135], v62, s[6:7] offset:16
	global_load_dwordx4 v[136:139], v62, s[8:9]
	global_load_dwordx4 v[140:143], v62, s[8:9] offset:16
	s_add_u32 s6, s6, 0x3000
	s_addc_u32 s7, s7, 0
	s_add_u32 s8, s8, 0x3000
	s_addc_u32 s9, s9, 0
	s_waitcnt vmcnt(16)
	v_add_f32_e32 v152, 1.0, v152
	v_add_f32_e32 v153, 1.0, v153
	v_add_f32_e32 v154, 1.0, v154
	v_add_f32_e32 v155, 1.0, v155
	v_add_f32_e32 v156, 1.0, v156
	v_add_f32_e32 v157, 1.0, v157
	v_add_f32_e32 v158, 1.0, v158
	v_add_f32_e32 v159, 1.0, v159
	s_waitcnt vmcnt(26)
	v_fma_f32 v96, v96, v152, v144
	v_fma_f32 v97, v97, v153, v145
	v_fma_f32 v98, v98, v154, v146
	v_fma_f32 v99, v99, v155, v147
	v_fma_f32 v100, v100, v156, v148
	v_fma_f32 v101, v101, v157, v149
	v_fma_f32 v102, v102, v158, v150
	v_fma_f32 v103, v103, v159, v151
	v_cvt_pk_bf16_f32 v96, v96, v97
	v_cvt_pk_bf16_f32 v97, v98, v99
	v_cvt_pk_bf16_f32 v98, v100, v101
	v_cvt_pk_bf16_f32 v99, v102, v103
	global_store_dwordx4 v61, v[96:99], s[4:5]
	s_add_u32 s4, s4, 0x200000
	s_addc_u32 s5, s5, 0
	global_load_dwordx4 v[96:99], v60, s[80:81] nt
	global_load_dwordx4 v[100:103], v60, s[80:81] offset:16 nt
	s_add_u32 s80, s80, 0x400000
	s_addc_u32 s81, s81, 0
	s_waitcnt vmcnt(27)
	v_fma_f32 v104, v104, v152, v144
	v_fma_f32 v105, v105, v153, v145
	v_fma_f32 v106, v106, v154, v146
	v_fma_f32 v107, v107, v155, v147
	v_fma_f32 v108, v108, v156, v148
	v_fma_f32 v109, v109, v157, v149
	v_fma_f32 v110, v110, v158, v150
	v_fma_f32 v111, v111, v159, v151
	v_cvt_pk_bf16_f32 v104, v104, v105
	v_cvt_pk_bf16_f32 v105, v106, v107
	v_cvt_pk_bf16_f32 v106, v108, v109
	v_cvt_pk_bf16_f32 v107, v110, v111
	global_store_dwordx4 v61, v[104:107], s[4:5]
	s_add_u32 s4, s4, 0x200000
	s_addc_u32 s5, s5, 0
	global_load_dwordx4 v[104:107], v60, s[80:81] nt
	global_load_dwordx4 v[108:111], v60, s[80:81] offset:16 nt
	s_add_u32 s80, s80, 0x400000
	s_addc_u32 s81, s81, 0
	s_waitcnt vmcnt(28)
	v_fma_f32 v112, v112, v152, v144
	v_fma_f32 v113, v113, v153, v145
	v_fma_f32 v114, v114, v154, v146
	v_fma_f32 v115, v115, v155, v147
	v_fma_f32 v116, v116, v156, v148
	v_fma_f32 v117, v117, v157, v149
	v_fma_f32 v118, v118, v158, v150
	v_fma_f32 v119, v119, v159, v151
	v_cvt_pk_bf16_f32 v112, v112, v113
	v_cvt_pk_bf16_f32 v113, v114, v115
	v_cvt_pk_bf16_f32 v114, v116, v117
	v_cvt_pk_bf16_f32 v115, v118, v119
	global_store_dwordx4 v61, v[112:115], s[4:5]
	s_add_u32 s4, s4, 0x200000
	s_addc_u32 s5, s5, 0
	global_load_dwordx4 v[112:115], v60, s[80:81] nt
	global_load_dwordx4 v[116:119], v60, s[80:81] offset:16 nt
	s_add_u32 s80, s80, 0x400000
	s_addc_u32 s81, s81, 0
	s_waitcnt vmcnt(29)
	v_fma_f32 v120, v120, v152, v144
	v_fma_f32 v121, v121, v153, v145
	v_fma_f32 v122, v122, v154, v146
	v_fma_f32 v123, v123, v155, v147
	v_fma_f32 v124, v124, v156, v148
	v_fma_f32 v125, v125, v157, v149
	v_fma_f32 v126, v126, v158, v150
	v_fma_f32 v127, v127, v159, v151
	v_cvt_pk_bf16_f32 v120, v120, v121
	v_cvt_pk_bf16_f32 v121, v122, v123
	v_cvt_pk_bf16_f32 v122, v124, v125
	v_cvt_pk_bf16_f32 v123, v126, v127
	global_store_dwordx4 v61, v[120:123], s[4:5]
	s_add_u32 s4, s4, 0x200000
	s_addc_u32 s5, s5, 0
	global_load_dwordx4 v[120:123], v60, s[80:81] nt
	global_load_dwordx4 v[124:127], v60, s[80:81] offset:16 nt
	s_add_u32 s80, s80, 0x400000
	s_addc_u32 s81, s81, 0
	global_load_dwordx4 v[144:147], v62, s[6:7]
	global_load_dwordx4 v[148:151], v62, s[6:7] offset:16
	global_load_dwordx4 v[152:155], v62, s[8:9]
	global_load_dwordx4 v[156:159], v62, s[8:9] offset:16
	s_add_u32 s6, s6, 0x3000
	s_addc_u32 s7, s7, 0
	s_add_u32 s8, s8, 0x3000
	s_addc_u32 s9, s9, 0
	s_waitcnt vmcnt(16)
	v_add_f32_e32 v136, 1.0, v136
	v_add_f32_e32 v137, 1.0, v137
	v_add_f32_e32 v138, 1.0, v138
	v_add_f32_e32 v139, 1.0, v139
	v_add_f32_e32 v140, 1.0, v140
	v_add_f32_e32 v141, 1.0, v141
	v_add_f32_e32 v142, 1.0, v142
	v_add_f32_e32 v143, 1.0, v143
	s_waitcnt vmcnt(29)
	v_fma_f32 v64, v64, v136, v128
	v_fma_f32 v65, v65, v137, v129
	v_fma_f32 v66, v66, v138, v130
	v_fma_f32 v67, v67, v139, v131
	v_fma_f32 v68, v68, v140, v132
	v_fma_f32 v69, v69, v141, v133
	v_fma_f32 v70, v70, v142, v134
	v_fma_f32 v71, v71, v143, v135
	v_cvt_pk_bf16_f32 v64, v64, v65
	v_cvt_pk_bf16_f32 v65, v66, v67
	v_cvt_pk_bf16_f32 v66, v68, v69
	v_cvt_pk_bf16_f32 v67, v70, v71
	global_store_dwordx4 v61, v[64:67], s[4:5]
	s_add_u32 s4, s4, 0x200000
	s_addc_u32 s5, s5, 0
	global_load_dwordx4 v[64:67], v60, s[80:81] nt
	global_load_dwordx4 v[68:71], v60, s[80:81] offset:16 nt
	s_add_u32 s80, s80, 0x400000
	s_addc_u32 s81, s81, 0
	s_waitcnt vmcnt(29)
	v_fma_f32 v72, v72, v136, v128
	v_fma_f32 v73, v73, v137, v129
	v_fma_f32 v74, v74, v138, v130
	v_fma_f32 v75, v75, v139, v131
	v_fma_f32 v76, v76, v140, v132
	v_fma_f32 v77, v77, v141, v133
	v_fma_f32 v78, v78, v142, v134
	v_fma_f32 v79, v79, v143, v135
	v_cvt_pk_bf16_f32 v72, v72, v73
	v_cvt_pk_bf16_f32 v73, v74, v75
	v_cvt_pk_bf16_f32 v74, v76, v77
	v_cvt_pk_bf16_f32 v75, v78, v79
	global_store_dwordx4 v61, v[72:75], s[4:5]
	s_add_u32 s4, s4, 0x200000
	s_addc_u32 s5, s5, 0
	global_load_dwordx4 v[72:75], v60, s[80:81] nt
	global_load_dwordx4 v[76:79], v60, s[80:81] offset:16 nt
	s_add_u32 s80, s80, 0x400000
	s_addc_u32 s81, s81, 0
	s_waitcnt vmcnt(29)
	v_fma_f32 v80, v80, v136, v128
	v_fma_f32 v81, v81, v137, v129
	v_fma_f32 v82, v82, v138, v130
	v_fma_f32 v83, v83, v139, v131
	v_fma_f32 v84, v84, v140, v132
	v_fma_f32 v85, v85, v141, v133
	v_fma_f32 v86, v86, v142, v134
	v_fma_f32 v87, v87, v143, v135
	v_cvt_pk_bf16_f32 v80, v80, v81
	v_cvt_pk_bf16_f32 v81, v82, v83
	v_cvt_pk_bf16_f32 v82, v84, v85
	v_cvt_pk_bf16_f32 v83, v86, v87
	global_store_dwordx4 v61, v[80:83], s[4:5]
	s_add_u32 s4, s4, 0x200000
	s_addc_u32 s5, s5, 0
	global_load_dwordx4 v[80:83], v60, s[80:81] nt
	global_load_dwordx4 v[84:87], v60, s[80:81] offset:16 nt
	s_add_u32 s80, s80, 0x400000
	s_addc_u32 s81, s81, 0
	s_waitcnt vmcnt(29)
	v_fma_f32 v88, v88, v136, v128
	v_fma_f32 v89, v89, v137, v129
	v_fma_f32 v90, v90, v138, v130
	v_fma_f32 v91, v91, v139, v131
	v_fma_f32 v92, v92, v140, v132
	v_fma_f32 v93, v93, v141, v133
	v_fma_f32 v94, v94, v142, v134
	v_fma_f32 v95, v95, v143, v135
	v_cvt_pk_bf16_f32 v88, v88, v89
	v_cvt_pk_bf16_f32 v89, v90, v91
	v_cvt_pk_bf16_f32 v90, v92, v93
	v_cvt_pk_bf16_f32 v91, v94, v95
	global_store_dwordx4 v61, v[88:91], s[4:5]
	s_add_u32 s4, s4, 0x200000
	s_addc_u32 s5, s5, 0
	global_load_dwordx4 v[88:91], v60, s[80:81] nt
	global_load_dwordx4 v[92:95], v60, s[80:81] offset:16 nt
	s_add_u32 s80, s80, 0x400000
	s_addc_u32 s81, s81, 0
	global_load_dwordx4 v[128:131], v62, s[6:7]
	global_load_dwordx4 v[132:135], v62, s[6:7] offset:16
	global_load_dwordx4 v[136:139], v62, s[8:9]
	global_load_dwordx4 v[140:143], v62, s[8:9] offset:16
	s_add_u32 s6, s6, 0x3000
	s_addc_u32 s7, s7, 0
	s_add_u32 s8, s8, 0x3000
	s_addc_u32 s9, s9, 0
	s_waitcnt vmcnt(16)
	v_add_f32_e32 v152, 1.0, v152
	v_add_f32_e32 v153, 1.0, v153
	v_add_f32_e32 v154, 1.0, v154
	v_add_f32_e32 v155, 1.0, v155
	v_add_f32_e32 v156, 1.0, v156
	v_add_f32_e32 v157, 1.0, v157
	v_add_f32_e32 v158, 1.0, v158
	v_add_f32_e32 v159, 1.0, v159
	s_waitcnt vmcnt(29)
	v_fma_f32 v96, v96, v152, v144
	v_fma_f32 v97, v97, v153, v145
	v_fma_f32 v98, v98, v154, v146
	v_fma_f32 v99, v99, v155, v147
	v_fma_f32 v100, v100, v156, v148
	v_fma_f32 v101, v101, v157, v149
	v_fma_f32 v102, v102, v158, v150
	v_fma_f32 v103, v103, v159, v151
	v_cvt_pk_bf16_f32 v96, v96, v97
	v_cvt_pk_bf16_f32 v97, v98, v99
	v_cvt_pk_bf16_f32 v98, v100, v101
	v_cvt_pk_bf16_f32 v99, v102, v103
	global_store_dwordx4 v61, v[96:99], s[4:5]
	s_add_u32 s4, s4, 0x200000
	s_addc_u32 s5, s5, 0
	global_load_dwordx4 v[96:99], v60, s[80:81] nt
	global_load_dwordx4 v[100:103], v60, s[80:81] offset:16 nt
	s_add_u32 s80, s80, 0x400000
	s_addc_u32 s81, s81, 0
	s_waitcnt vmcnt(29)
	v_fma_f32 v104, v104, v152, v144
	v_fma_f32 v105, v105, v153, v145
	v_fma_f32 v106, v106, v154, v146
	v_fma_f32 v107, v107, v155, v147
	v_fma_f32 v108, v108, v156, v148
	v_fma_f32 v109, v109, v157, v149
	v_fma_f32 v110, v110, v158, v150
	v_fma_f32 v111, v111, v159, v151
	v_cvt_pk_bf16_f32 v104, v104, v105
	v_cvt_pk_bf16_f32 v105, v106, v107
	v_cvt_pk_bf16_f32 v106, v108, v109
	v_cvt_pk_bf16_f32 v107, v110, v111
	global_store_dwordx4 v61, v[104:107], s[4:5]
	s_add_u32 s4, s4, 0x200000
	s_addc_u32 s5, s5, 0
	global_load_dwordx4 v[104:107], v60, s[80:81] nt
	global_load_dwordx4 v[108:111], v60, s[80:81] offset:16 nt
	s_add_u32 s80, s80, 0x400000
	s_addc_u32 s81, s81, 0
	s_waitcnt vmcnt(29)
	v_fma_f32 v112, v112, v152, v144
	v_fma_f32 v113, v113, v153, v145
	v_fma_f32 v114, v114, v154, v146
	v_fma_f32 v115, v115, v155, v147
	v_fma_f32 v116, v116, v156, v148
	v_fma_f32 v117, v117, v157, v149
	v_fma_f32 v118, v118, v158, v150
	v_fma_f32 v119, v119, v159, v151
	v_cvt_pk_bf16_f32 v112, v112, v113
	v_cvt_pk_bf16_f32 v113, v114, v115
	v_cvt_pk_bf16_f32 v114, v116, v117
	v_cvt_pk_bf16_f32 v115, v118, v119
	global_store_dwordx4 v61, v[112:115], s[4:5]
	s_add_u32 s4, s4, 0x200000
	s_addc_u32 s5, s5, 0
	global_load_dwordx4 v[112:115], v60, s[80:81] nt
	global_load_dwordx4 v[116:119], v60, s[80:81] offset:16 nt
	s_add_u32 s80, s80, 0x400000
	s_addc_u32 s81, s81, 0
	s_waitcnt vmcnt(29)
	v_fma_f32 v120, v120, v152, v144
	v_fma_f32 v121, v121, v153, v145
	v_fma_f32 v122, v122, v154, v146
	v_fma_f32 v123, v123, v155, v147
	v_fma_f32 v124, v124, v156, v148
	v_fma_f32 v125, v125, v157, v149
	v_fma_f32 v126, v126, v158, v150
	v_fma_f32 v127, v127, v159, v151
	v_cvt_pk_bf16_f32 v120, v120, v121
	v_cvt_pk_bf16_f32 v121, v122, v123
	v_cvt_pk_bf16_f32 v122, v124, v125
	v_cvt_pk_bf16_f32 v123, v126, v127
	global_store_dwordx4 v61, v[120:123], s[4:5]
	s_add_u32 s4, s4, 0x200000
	s_addc_u32 s5, s5, 0
	global_load_dwordx4 v[120:123], v60, s[80:81] nt
	global_load_dwordx4 v[124:127], v60, s[80:81] offset:16 nt
	s_add_u32 s80, s80, 0x400000
	s_addc_u32 s81, s81, 0
	global_load_dwordx4 v[144:147], v62, s[6:7]
	global_load_dwordx4 v[148:151], v62, s[6:7] offset:16
	global_load_dwordx4 v[152:155], v62, s[8:9]
	global_load_dwordx4 v[156:159], v62, s[8:9] offset:16
	s_add_u32 s6, s6, 0x3000
	s_addc_u32 s7, s7, 0
	s_add_u32 s8, s8, 0x3000
	s_addc_u32 s9, s9, 0
	s_waitcnt vmcnt(16)
	v_add_f32_e32 v136, 1.0, v136
	v_add_f32_e32 v137, 1.0, v137
	v_add_f32_e32 v138, 1.0, v138
	v_add_f32_e32 v139, 1.0, v139
	v_add_f32_e32 v140, 1.0, v140
	v_add_f32_e32 v141, 1.0, v141
	v_add_f32_e32 v142, 1.0, v142
	v_add_f32_e32 v143, 1.0, v143
	s_waitcnt vmcnt(29)
	v_fma_f32 v64, v64, v136, v128
	v_fma_f32 v65, v65, v137, v129
	v_fma_f32 v66, v66, v138, v130
	v_fma_f32 v67, v67, v139, v131
	v_fma_f32 v68, v68, v140, v132
	v_fma_f32 v69, v69, v141, v133
	v_fma_f32 v70, v70, v142, v134
	v_fma_f32 v71, v71, v143, v135
	v_cvt_pk_bf16_f32 v64, v64, v65
	v_cvt_pk_bf16_f32 v65, v66, v67
	v_cvt_pk_bf16_f32 v66, v68, v69
	v_cvt_pk_bf16_f32 v67, v70, v71
	global_store_dwordx4 v61, v[64:67], s[4:5]
	s_add_u32 s4, s4, 0x200000
	s_addc_u32 s5, s5, 0
	global_load_dwordx4 v[64:67], v60, s[80:81] nt
	global_load_dwordx4 v[68:71], v60, s[80:81] offset:16 nt
	s_add_u32 s80, s80, 0x400000
	s_addc_u32 s81, s81, 0
	s_waitcnt vmcnt(29)
	v_fma_f32 v72, v72, v136, v128
	v_fma_f32 v73, v73, v137, v129
	v_fma_f32 v74, v74, v138, v130
	v_fma_f32 v75, v75, v139, v131
	v_fma_f32 v76, v76, v140, v132
	v_fma_f32 v77, v77, v141, v133
	v_fma_f32 v78, v78, v142, v134
	v_fma_f32 v79, v79, v143, v135
	v_cvt_pk_bf16_f32 v72, v72, v73
	v_cvt_pk_bf16_f32 v73, v74, v75
	v_cvt_pk_bf16_f32 v74, v76, v77
	v_cvt_pk_bf16_f32 v75, v78, v79
	global_store_dwordx4 v61, v[72:75], s[4:5]
	s_add_u32 s4, s4, 0x200000
	s_addc_u32 s5, s5, 0
	global_load_dwordx4 v[72:75], v60, s[80:81] nt
	global_load_dwordx4 v[76:79], v60, s[80:81] offset:16 nt
	s_add_u32 s80, s80, 0x400000
	s_addc_u32 s81, s81, 0
	s_waitcnt vmcnt(29)
	v_fma_f32 v80, v80, v136, v128
	v_fma_f32 v81, v81, v137, v129
	v_fma_f32 v82, v82, v138, v130
	v_fma_f32 v83, v83, v139, v131
	v_fma_f32 v84, v84, v140, v132
	v_fma_f32 v85, v85, v141, v133
	v_fma_f32 v86, v86, v142, v134
	v_fma_f32 v87, v87, v143, v135
	v_cvt_pk_bf16_f32 v80, v80, v81
	v_cvt_pk_bf16_f32 v81, v82, v83
	v_cvt_pk_bf16_f32 v82, v84, v85
	v_cvt_pk_bf16_f32 v83, v86, v87
	global_store_dwordx4 v61, v[80:83], s[4:5]
	s_add_u32 s4, s4, 0x200000
	s_addc_u32 s5, s5, 0
	global_load_dwordx4 v[80:83], v60, s[80:81] nt
	global_load_dwordx4 v[84:87], v60, s[80:81] offset:16 nt
	s_add_u32 s80, s80, 0x400000
	s_addc_u32 s81, s81, 0
	s_waitcnt vmcnt(29)
	v_fma_f32 v88, v88, v136, v128
	v_fma_f32 v89, v89, v137, v129
	v_fma_f32 v90, v90, v138, v130
	v_fma_f32 v91, v91, v139, v131
	v_fma_f32 v92, v92, v140, v132
	v_fma_f32 v93, v93, v141, v133
	v_fma_f32 v94, v94, v142, v134
	v_fma_f32 v95, v95, v143, v135
	v_cvt_pk_bf16_f32 v88, v88, v89
	v_cvt_pk_bf16_f32 v89, v90, v91
	v_cvt_pk_bf16_f32 v90, v92, v93
	v_cvt_pk_bf16_f32 v91, v94, v95
	global_store_dwordx4 v61, v[88:91], s[4:5]
	s_add_u32 s4, s4, 0x200000
	s_addc_u32 s5, s5, 0
	global_load_dwordx4 v[88:91], v60, s[80:81] nt
	global_load_dwordx4 v[92:95], v60, s[80:81] offset:16 nt
	s_add_u32 s80, s80, 0x400000
	s_addc_u32 s81, s81, 0
	global_load_dwordx4 v[128:131], v62, s[6:7]
	global_load_dwordx4 v[132:135], v62, s[6:7] offset:16
	global_load_dwordx4 v[136:139], v62, s[8:9]
	global_load_dwordx4 v[140:143], v62, s[8:9] offset:16
	s_add_u32 s6, s6, 0x3000
	s_addc_u32 s7, s7, 0
	s_add_u32 s8, s8, 0x3000
	s_addc_u32 s9, s9, 0
	s_waitcnt vmcnt(16)
	v_add_f32_e32 v152, 1.0, v152
	v_add_f32_e32 v153, 1.0, v153
	v_add_f32_e32 v154, 1.0, v154
	v_add_f32_e32 v155, 1.0, v155
	v_add_f32_e32 v156, 1.0, v156
	v_add_f32_e32 v157, 1.0, v157
	v_add_f32_e32 v158, 1.0, v158
	v_add_f32_e32 v159, 1.0, v159
	s_waitcnt vmcnt(29)
	v_fma_f32 v96, v96, v152, v144
	v_fma_f32 v97, v97, v153, v145
	v_fma_f32 v98, v98, v154, v146
	v_fma_f32 v99, v99, v155, v147
	v_fma_f32 v100, v100, v156, v148
	v_fma_f32 v101, v101, v157, v149
	v_fma_f32 v102, v102, v158, v150
	v_fma_f32 v103, v103, v159, v151
	v_cvt_pk_bf16_f32 v96, v96, v97
	v_cvt_pk_bf16_f32 v97, v98, v99
	v_cvt_pk_bf16_f32 v98, v100, v101
	v_cvt_pk_bf16_f32 v99, v102, v103
	global_store_dwordx4 v61, v[96:99], s[4:5]
	s_add_u32 s4, s4, 0x200000
	s_addc_u32 s5, s5, 0
	global_load_dwordx4 v[96:99], v60, s[80:81] nt
	global_load_dwordx4 v[100:103], v60, s[80:81] offset:16 nt
	s_add_u32 s80, s80, 0x400000
	s_addc_u32 s81, s81, 0
	s_waitcnt vmcnt(29)
	v_fma_f32 v104, v104, v152, v144
	v_fma_f32 v105, v105, v153, v145
	v_fma_f32 v106, v106, v154, v146
	v_fma_f32 v107, v107, v155, v147
	v_fma_f32 v108, v108, v156, v148
	v_fma_f32 v109, v109, v157, v149
	v_fma_f32 v110, v110, v158, v150
	v_fma_f32 v111, v111, v159, v151
	v_cvt_pk_bf16_f32 v104, v104, v105
	v_cvt_pk_bf16_f32 v105, v106, v107
	v_cvt_pk_bf16_f32 v106, v108, v109
	v_cvt_pk_bf16_f32 v107, v110, v111
	global_store_dwordx4 v61, v[104:107], s[4:5]
	s_add_u32 s4, s4, 0x200000
	s_addc_u32 s5, s5, 0
	global_load_dwordx4 v[104:107], v60, s[80:81] nt
	global_load_dwordx4 v[108:111], v60, s[80:81] offset:16 nt
	s_add_u32 s80, s80, 0x400000
	s_addc_u32 s81, s81, 0
	s_waitcnt vmcnt(29)
	v_fma_f32 v112, v112, v152, v144
	v_fma_f32 v113, v113, v153, v145
	v_fma_f32 v114, v114, v154, v146
	v_fma_f32 v115, v115, v155, v147
	v_fma_f32 v116, v116, v156, v148
	v_fma_f32 v117, v117, v157, v149
	v_fma_f32 v118, v118, v158, v150
	v_fma_f32 v119, v119, v159, v151
	v_cvt_pk_bf16_f32 v112, v112, v113
	v_cvt_pk_bf16_f32 v113, v114, v115
	v_cvt_pk_bf16_f32 v114, v116, v117
	v_cvt_pk_bf16_f32 v115, v118, v119
	global_store_dwordx4 v61, v[112:115], s[4:5]
	s_add_u32 s4, s4, 0x200000
	s_addc_u32 s5, s5, 0
	global_load_dwordx4 v[112:115], v60, s[80:81] nt
	global_load_dwordx4 v[116:119], v60, s[80:81] offset:16 nt
	s_add_u32 s80, s80, 0x400000
	s_addc_u32 s81, s81, 0
	s_waitcnt vmcnt(29)
	v_fma_f32 v120, v120, v152, v144
	v_fma_f32 v121, v121, v153, v145
	v_fma_f32 v122, v122, v154, v146
	v_fma_f32 v123, v123, v155, v147
	v_fma_f32 v124, v124, v156, v148
	v_fma_f32 v125, v125, v157, v149
	v_fma_f32 v126, v126, v158, v150
	v_fma_f32 v127, v127, v159, v151
	v_cvt_pk_bf16_f32 v120, v120, v121
	v_cvt_pk_bf16_f32 v121, v122, v123
	v_cvt_pk_bf16_f32 v122, v124, v125
	v_cvt_pk_bf16_f32 v123, v126, v127
	global_store_dwordx4 v61, v[120:123], s[4:5]
	s_add_u32 s4, s4, 0x200000
	s_addc_u32 s5, s5, 0
	global_load_dwordx4 v[120:123], v60, s[80:81] nt
	global_load_dwordx4 v[124:127], v60, s[80:81] offset:16 nt
	s_add_u32 s80, s80, 0x400000
	s_addc_u32 s81, s81, 0
	global_load_dwordx4 v[144:147], v62, s[6:7]
	global_load_dwordx4 v[148:151], v62, s[6:7] offset:16
	global_load_dwordx4 v[152:155], v62, s[8:9]
	global_load_dwordx4 v[156:159], v62, s[8:9] offset:16
	s_add_u32 s6, s6, 0x3000
	s_addc_u32 s7, s7, 0
	s_add_u32 s8, s8, 0x3000
	s_addc_u32 s9, s9, 0
	s_waitcnt vmcnt(16)
	v_add_f32_e32 v136, 1.0, v136
	v_add_f32_e32 v137, 1.0, v137
	v_add_f32_e32 v138, 1.0, v138
	v_add_f32_e32 v139, 1.0, v139
	v_add_f32_e32 v140, 1.0, v140
	v_add_f32_e32 v141, 1.0, v141
	v_add_f32_e32 v142, 1.0, v142
	v_add_f32_e32 v143, 1.0, v143
	s_waitcnt vmcnt(29)
	v_fma_f32 v64, v64, v136, v128
	v_fma_f32 v65, v65, v137, v129
	v_fma_f32 v66, v66, v138, v130
	v_fma_f32 v67, v67, v139, v131
	v_fma_f32 v68, v68, v140, v132
	v_fma_f32 v69, v69, v141, v133
	v_fma_f32 v70, v70, v142, v134
	v_fma_f32 v71, v71, v143, v135
	v_cvt_pk_bf16_f32 v64, v64, v65
	v_cvt_pk_bf16_f32 v65, v66, v67
	v_cvt_pk_bf16_f32 v66, v68, v69
	v_cvt_pk_bf16_f32 v67, v70, v71
	global_store_dwordx4 v61, v[64:67], s[4:5]
	s_add_u32 s4, s4, 0x200000
	s_addc_u32 s5, s5, 0
	s_waitcnt vmcnt(27)
	v_fma_f32 v72, v72, v136, v128
	v_fma_f32 v73, v73, v137, v129
	v_fma_f32 v74, v74, v138, v130
	v_fma_f32 v75, v75, v139, v131
	v_fma_f32 v76, v76, v140, v132
	v_fma_f32 v77, v77, v141, v133
	v_fma_f32 v78, v78, v142, v134
	v_fma_f32 v79, v79, v143, v135
	v_cvt_pk_bf16_f32 v72, v72, v73
	v_cvt_pk_bf16_f32 v73, v74, v75
	v_cvt_pk_bf16_f32 v74, v76, v77
	v_cvt_pk_bf16_f32 v75, v78, v79
	global_store_dwordx4 v61, v[72:75], s[4:5]
	s_add_u32 s4, s4, 0x200000
	s_addc_u32 s5, s5, 0
	s_waitcnt vmcnt(25)
	v_fma_f32 v80, v80, v136, v128
	v_fma_f32 v81, v81, v137, v129
	v_fma_f32 v82, v82, v138, v130
	v_fma_f32 v83, v83, v139, v131
	v_fma_f32 v84, v84, v140, v132
	v_fma_f32 v85, v85, v141, v133
	v_fma_f32 v86, v86, v142, v134
	v_fma_f32 v87, v87, v143, v135
	v_cvt_pk_bf16_f32 v80, v80, v81
	v_cvt_pk_bf16_f32 v81, v82, v83
	v_cvt_pk_bf16_f32 v82, v84, v85
	v_cvt_pk_bf16_f32 v83, v86, v87
	global_store_dwordx4 v61, v[80:83], s[4:5]
	s_add_u32 s4, s4, 0x200000
	s_addc_u32 s5, s5, 0
	s_waitcnt vmcnt(23)
	v_fma_f32 v88, v88, v136, v128
	v_fma_f32 v89, v89, v137, v129
	v_fma_f32 v90, v90, v138, v130
	v_fma_f32 v91, v91, v139, v131
	v_fma_f32 v92, v92, v140, v132
	v_fma_f32 v93, v93, v141, v133
	v_fma_f32 v94, v94, v142, v134
	v_fma_f32 v95, v95, v143, v135
	v_cvt_pk_bf16_f32 v88, v88, v89
	v_cvt_pk_bf16_f32 v89, v90, v91
	v_cvt_pk_bf16_f32 v90, v92, v93
	v_cvt_pk_bf16_f32 v91, v94, v95
	global_store_dwordx4 v61, v[88:91], s[4:5]
	s_add_u32 s4, s4, 0x200000
	s_addc_u32 s5, s5, 0
	s_waitcnt vmcnt(4)
	v_add_f32_e32 v152, 1.0, v152
	v_add_f32_e32 v153, 1.0, v153
	v_add_f32_e32 v154, 1.0, v154
	v_add_f32_e32 v155, 1.0, v155
	v_add_f32_e32 v156, 1.0, v156
	v_add_f32_e32 v157, 1.0, v157
	v_add_f32_e32 v158, 1.0, v158
	v_add_f32_e32 v159, 1.0, v159
	s_waitcnt vmcnt(17)
	v_fma_f32 v96, v96, v152, v144
	v_fma_f32 v97, v97, v153, v145
	v_fma_f32 v98, v98, v154, v146
	v_fma_f32 v99, v99, v155, v147
	v_fma_f32 v100, v100, v156, v148
	v_fma_f32 v101, v101, v157, v149
	v_fma_f32 v102, v102, v158, v150
	v_fma_f32 v103, v103, v159, v151
	v_cvt_pk_bf16_f32 v96, v96, v97
	v_cvt_pk_bf16_f32 v97, v98, v99
	v_cvt_pk_bf16_f32 v98, v100, v101
	v_cvt_pk_bf16_f32 v99, v102, v103
	global_store_dwordx4 v61, v[96:99], s[4:5]
	s_add_u32 s4, s4, 0x200000
	s_addc_u32 s5, s5, 0
	s_waitcnt vmcnt(15)
	v_fma_f32 v104, v104, v152, v144
	v_fma_f32 v105, v105, v153, v145
	v_fma_f32 v106, v106, v154, v146
	v_fma_f32 v107, v107, v155, v147
	v_fma_f32 v108, v108, v156, v148
	v_fma_f32 v109, v109, v157, v149
	v_fma_f32 v110, v110, v158, v150
	v_fma_f32 v111, v111, v159, v151
	v_cvt_pk_bf16_f32 v104, v104, v105
	v_cvt_pk_bf16_f32 v105, v106, v107
	v_cvt_pk_bf16_f32 v106, v108, v109
	v_cvt_pk_bf16_f32 v107, v110, v111
	global_store_dwordx4 v61, v[104:107], s[4:5]
	s_add_u32 s4, s4, 0x200000
	s_addc_u32 s5, s5, 0
	s_waitcnt vmcnt(13)
	v_fma_f32 v112, v112, v152, v144
	v_fma_f32 v113, v113, v153, v145
	v_fma_f32 v114, v114, v154, v146
	v_fma_f32 v115, v115, v155, v147
	v_fma_f32 v116, v116, v156, v148
	v_fma_f32 v117, v117, v157, v149
	v_fma_f32 v118, v118, v158, v150
	v_fma_f32 v119, v119, v159, v151
	v_cvt_pk_bf16_f32 v112, v112, v113
	v_cvt_pk_bf16_f32 v113, v114, v115
	v_cvt_pk_bf16_f32 v114, v116, v117
	v_cvt_pk_bf16_f32 v115, v118, v119
	global_store_dwordx4 v61, v[112:115], s[4:5]
	s_add_u32 s4, s4, 0x200000
	s_addc_u32 s5, s5, 0
	s_waitcnt vmcnt(11)
	v_fma_f32 v120, v120, v152, v144
	v_fma_f32 v121, v121, v153, v145
	v_fma_f32 v122, v122, v154, v146
	v_fma_f32 v123, v123, v155, v147
	v_fma_f32 v124, v124, v156, v148
	v_fma_f32 v125, v125, v157, v149
	v_fma_f32 v126, v126, v158, v150
	v_fma_f32 v127, v127, v159, v151
	v_cvt_pk_bf16_f32 v120, v120, v121
	v_cvt_pk_bf16_f32 v121, v122, v123
	v_cvt_pk_bf16_f32 v122, v124, v125
	v_cvt_pk_bf16_f32 v123, v126, v127
	global_store_dwordx4 v61, v[120:123], s[4:5]
	s_add_u32 s4, s4, 0x200000
	s_addc_u32 s5, s5, 0
	s_branch .LBB0_180
.Lp1_orig:
	s_branch .LBB0_168
.LBB0_167:
	s_or_b64 exec, exec, s[4:5]
	s_add_u32 s82, s82, s24
	s_addc_u32 s83, s83, s25
	v_lshl_add_u64 v[32:33], v[32:33], 0, s[22:23]
	s_add_u32 s80, s80, s60
	s_addc_u32 s81, s81, s61
	v_cmp_lt_u64_e32 vcc, s[78:79], v[32:33]
	s_or_b64 s[74:75], vcc, s[74:75]
	v_lshl_add_u64 v[36:37], v[36:37], 0, s[50:51]
	s_andn2_b64 exec, exec, s[74:75]
	s_cbranch_execz .LBB0_180
